# attention task epilogues: the 8 gate loads batched ahead of the scale/store sequence (loads cross the stores to other buffers)
# speedup vs baseline: 1.0072x; 1.0049x over previous
; DI unsigned pk2(float a, float b) { f2_t v = {a, b}; return __builtin_bit_cast(unsigned, __builtin_convertvector(v, bf2_t)); }
; DI float bflo(unsigned x) { return __uint_as_float(x << 16); }
; DI float bfhi(unsigned x) { return __uint_as_float(x & 0xffff0000u); }
; template <int DK, bool SB> ...
;     ...
;   if (wave_active && slot < nq_valid) {
;     float sc = 1.f;
;     if (!SB) { float lt = l_run + __shfl_xor(l_run, 32); sc = 1.f / lt; }
; #pragma unroll
;     for (int bd = 0; bd < 2; bd++)
; #pragma unroll
;       for (int g = 0; g < 4; g++) {
;         int d0 = bd * 32 + 8 * g + 4 * hl;
;         uint2 zz = *(const uint2*)(Zp + (size_t)slot * 512 + d0);
;         uint2 o;
;         o.x = pk2(O[bd][4 * g] * sc * bflo(zz.x), O[bd][4 * g + 1] * sc * bfhi(zz.x));
;         o.y = pk2(O[bd][4 * g + 2] * sc * bflo(zz.y), O[bd][4 * g + 3] * sc * bfhi(zz.y));
;         *(uint2*)(Yp + (size_t)slot * 512 + d0) = o;
;       }
;   }
.LBB0_809:
	s_and_b64 s[4:5], s[4:5], vcc
	s_and_saveexec_b64 s[6:7], s[4:5]
	s_xor_b64 s[4:5], exec, s[6:7]
	s_cbranch_execz .LBB0_811
	s_lshl_b64 s[6:7], s[2:3], 1
	v_cmp_lt_i32_e32 vcc, v197, v196
	s_add_u32 s8, s6, 0x1020000
	s_addc_u32 s9, s7, 0
	v_cndmask_b32_e32 v32, v194, v197, vcc
	v_lshlrev_b32_e32 v32, 2, v32
	s_add_u32 s6, s84, s8
	ds_bpermute_b32 v32, v32, v124
	s_addc_u32 s7, s85, s9
	s_lshl_b32 s10, s54, 7
	s_add_u32 s6, s6, s10
	s_addc_u32 s7, s7, 0
	v_readlane_b32 s12, v254, 39
	v_readlane_b32 s13, v254, 40
	s_add_u32 s8, s12, s8
	s_addc_u32 s9, s13, s9
	s_waitcnt lgkmcnt(0)
	v_add_f32_e32 v32, v124, v32
	s_add_u32 s8, s8, s10
	v_div_scale_f32 v33, s[10:11], v32, v32, 1.0
	v_rcp_f32_e32 v34, v33
	v_ashrrev_i32_e32 v109, 31, v108
	s_addc_u32 s9, s9, 0
	v_lshlrev_b32_e32 v162, 1, v119
	v_fma_f32 v35, -v33, v34, 1.0
	v_fmac_f32_e32 v34, v35, v34
	v_div_scale_f32 v35, vcc, 1.0, v32, 1.0
	v_mul_f32_e32 v36, v35, v34
	v_fma_f32 v37, -v33, v36, v35
	v_fmac_f32_e32 v36, v37, v34
	v_fma_f32 v33, -v33, v36, v35
	v_div_fmas_f32 v33, v33, v34, v36
	v_lshlrev_b64 v[34:35], 10, v[108:109]
	v_lshl_add_u64 v[36:37], s[8:9], 0, v[34:35]
	v_lshl_add_u64 v[38:39], s[6:7], 0, v[34:35]
	v_lshl_add_u64 v[34:35], v[36:37], 0, v[162:163]
	global_load_dwordx2 v[42:43], v[34:35], off
	global_load_dwordx2 v[50:51], v[34:35], off offset:16
	global_load_dwordx2 v[58:59], v[34:35], off offset:32
	global_load_dwordx2 v[62:63], v[34:35], off offset:48
	global_load_dwordx2 v[66:67], v[34:35], off offset:64
	global_load_dwordx2 v[70:71], v[34:35], off offset:80
	global_load_dwordx2 v[74:75], v[34:35], off offset:96
	global_load_dwordx2 v[78:79], v[34:35], off offset:112
	v_div_fixup_f32 v32, v33, v32, 1.0
	v_pk_mul_f32 v[16:17], v[16:17], v[32:33] op_sel_hi:[1,0]
	v_pk_mul_f32 v[18:19], v[18:19], v[32:33] op_sel_hi:[1,0]
	v_pk_mul_f32 v[20:21], v[20:21], v[32:33] op_sel_hi:[1,0]
	v_pk_mul_f32 v[22:23], v[22:23], v[32:33] op_sel_hi:[1,0]
	v_pk_mul_f32 v[0:1], v[0:1], v[32:33] op_sel_hi:[1,0]
	v_pk_mul_f32 v[2:3], v[2:3], v[32:33] op_sel_hi:[1,0]
	v_pk_mul_f32 v[4:5], v[4:5], v[32:33] op_sel_hi:[1,0]
	s_waitcnt vmcnt(7)
	v_lshlrev_b32_e32 v40, 16, v42
	v_and_b32_e32 v41, 0xffff0000, v42
	v_pk_mul_f32 v[16:17], v[16:17], v[40:41]
	s_nop 0
	v_cvt_pk_bf16_f32 v36, v16, v17
	v_lshlrev_b32_e32 v16, 16, v43
	v_and_b32_e32 v17, 0xffff0000, v43
	v_pk_mul_f32 v[16:17], v[18:19], v[16:17]
	s_nop 0
	v_cvt_pk_bf16_f32 v37, v16, v17
	v_lshl_add_u64 v[16:17], v[38:39], 0, v[162:163]
	global_store_dwordx2 v[16:17], v[36:37], off
	s_waitcnt vmcnt(7)
	v_lshlrev_b32_e32 v36, 16, v50
	v_and_b32_e32 v37, 0xffff0000, v50
	v_pk_mul_f32 v[20:21], v[20:21], v[36:37]
	s_nop 0
	v_cvt_pk_bf16_f32 v18, v20, v21
	v_lshlrev_b32_e32 v20, 16, v51
	v_and_b32_e32 v21, 0xffff0000, v51
	v_pk_mul_f32 v[20:21], v[22:23], v[20:21]
	v_pk_mul_f32 v[22:23], v[24:25], v[32:33] op_sel_hi:[1,0]
	v_cvt_pk_bf16_f32 v19, v20, v21
	global_store_dwordx2 v[16:17], v[18:19], off offset:16
	s_nop 0
	s_waitcnt vmcnt(5)
	v_lshlrev_b32_e32 v20, 16, v58
	v_and_b32_e32 v21, 0xffff0000, v58
	v_pk_mul_f32 v[20:21], v[22:23], v[20:21]
	v_pk_mul_f32 v[22:23], v[26:27], v[32:33] op_sel_hi:[1,0]
	v_cvt_pk_bf16_f32 v18, v20, v21
	v_lshlrev_b32_e32 v20, 16, v59
	v_and_b32_e32 v21, 0xffff0000, v59
	v_pk_mul_f32 v[20:21], v[22:23], v[20:21]
	v_pk_mul_f32 v[22:23], v[28:29], v[32:33] op_sel_hi:[1,0]
	v_cvt_pk_bf16_f32 v19, v20, v21
	global_store_dwordx2 v[16:17], v[18:19], off offset:32
	s_nop 0
	s_waitcnt vmcnt(4)
	v_lshlrev_b32_e32 v20, 16, v62
	v_and_b32_e32 v21, 0xffff0000, v62
	v_pk_mul_f32 v[20:21], v[22:23], v[20:21]
	v_pk_mul_f32 v[22:23], v[30:31], v[32:33] op_sel_hi:[1,0]
	v_cvt_pk_bf16_f32 v18, v20, v21
	v_lshlrev_b32_e32 v20, 16, v63
	v_and_b32_e32 v21, 0xffff0000, v63
	v_pk_mul_f32 v[20:21], v[22:23], v[20:21]
	s_nop 0
	v_cvt_pk_bf16_f32 v19, v20, v21
	global_store_dwordx2 v[16:17], v[18:19], off offset:48
	s_nop 0
	s_waitcnt vmcnt(3)
	v_lshlrev_b32_e32 v20, 16, v66
	v_and_b32_e32 v21, 0xffff0000, v66
	v_lshlrev_b32_e32 v18, 16, v67
	v_and_b32_e32 v19, 0xffff0000, v67
	v_pk_mul_f32 v[0:1], v[0:1], v[20:21]
	v_pk_mul_f32 v[2:3], v[2:3], v[18:19]
	v_cvt_pk_bf16_f32 v0, v0, v1
	v_cvt_pk_bf16_f32 v1, v2, v3
	global_store_dwordx2 v[16:17], v[0:1], off offset:64
	s_nop 0
	s_waitcnt vmcnt(2)
	v_lshlrev_b32_e32 v2, 16, v70
	v_and_b32_e32 v3, 0xffff0000, v70
	v_pk_mul_f32 v[2:3], v[4:5], v[2:3]
	v_pk_mul_f32 v[4:5], v[6:7], v[32:33] op_sel_hi:[1,0]
	v_cvt_pk_bf16_f32 v0, v2, v3
	v_lshlrev_b32_e32 v2, 16, v71
	v_and_b32_e32 v3, 0xffff0000, v71
	v_pk_mul_f32 v[2:3], v[4:5], v[2:3]
	v_pk_mul_f32 v[4:5], v[8:9], v[32:33] op_sel_hi:[1,0]
	v_cvt_pk_bf16_f32 v1, v2, v3
	global_store_dwordx2 v[16:17], v[0:1], off offset:80
	s_nop 0
	s_waitcnt vmcnt(1)
	v_lshlrev_b32_e32 v2, 16, v74
	v_and_b32_e32 v3, 0xffff0000, v74
	v_pk_mul_f32 v[2:3], v[4:5], v[2:3]
	v_pk_mul_f32 v[4:5], v[10:11], v[32:33] op_sel_hi:[1,0]
	v_cvt_pk_bf16_f32 v0, v2, v3
	v_lshlrev_b32_e32 v2, 16, v75
	v_and_b32_e32 v3, 0xffff0000, v75
	v_pk_mul_f32 v[2:3], v[4:5], v[2:3]
	v_pk_mul_f32 v[4:5], v[12:13], v[32:33] op_sel_hi:[1,0]
	v_cvt_pk_bf16_f32 v1, v2, v3
	global_store_dwordx2 v[16:17], v[0:1], off offset:96
	s_nop 0
	s_waitcnt vmcnt(0)
	v_lshlrev_b32_e32 v2, 16, v78
	v_and_b32_e32 v3, 0xffff0000, v78
	v_pk_mul_f32 v[2:3], v[4:5], v[2:3]
	v_pk_mul_f32 v[4:5], v[14:15], v[32:33] op_sel_hi:[1,0]
	v_cvt_pk_bf16_f32 v0, v2, v3
	v_lshlrev_b32_e32 v2, 16, v79
	v_and_b32_e32 v3, 0xffff0000, v79
	v_pk_mul_f32 v[2:3], v[4:5], v[2:3]
	s_nop 0
	v_cvt_pk_bf16_f32 v1, v2, v3
	global_store_dwordx2 v[16:17], v[0:1], off offset:112

; DI unsigned pk2(float a, float b) { f2_t v = {a, b}; return __builtin_bit_cast(unsigned, __builtin_convertvector(v, bf2_t)); }
; DI float bflo(unsigned x) { return __uint_as_float(x << 16); }
; DI float bfhi(unsigned x) { return __uint_as_float(x & 0xffff0000u); }
; template <int DK, bool SB> ...
;     ...
;   if (wave_active && slot < nq_valid) {
;     float sc = 1.f;
;     if (!SB) { float lt = l_run + __shfl_xor(l_run, 32); sc = 1.f / lt; }
; #pragma unroll
;     for (int bd = 0; bd < 2; bd++)
; #pragma unroll
;       for (int g = 0; g < 4; g++) {
;         int d0 = bd * 32 + 8 * g + 4 * hl;
;         uint2 zz = *(const uint2*)(Zp + (size_t)slot * 512 + d0);
;         uint2 o;
;         o.x = pk2(O[bd][4 * g] * sc * bflo(zz.x), O[bd][4 * g + 1] * sc * bfhi(zz.x));
;         o.y = pk2(O[bd][4 * g + 2] * sc * bflo(zz.y), O[bd][4 * g + 3] * sc * bfhi(zz.y));
;         *(uint2*)(Yp + (size_t)slot * 512 + d0) = o;
;       }
;   }
.LBB0_829:
	s_and_saveexec_b64 s[4:5], s[10:11]
	s_xor_b64 s[4:5], exec, s[4:5]
	s_cbranch_execz .LBB0_831
	s_lshl_b64 s[2:3], s[2:3], 1
	s_add_u32 s6, s2, 0x2040000
	s_addc_u32 s7, s3, 0
	v_readlane_b32 s2, v254, 39
	v_readlane_b32 s3, v254, 40
	s_add_u32 s2, s2, s6
	s_addc_u32 s3, s3, s7
	s_lshl_b32 s8, s16, 1
	s_add_u32 s2, s2, s8
	s_addc_u32 s3, s3, 0
	s_add_u32 s6, s84, s6
	s_addc_u32 s7, s85, s7
	v_ashrrev_i32_e32 v97, 31, v96
	s_add_u32 s6, s6, s8
	v_lshlrev_b64 v[32:33], 10, v[96:97]
	s_addc_u32 s7, s7, 0
	v_lshl_add_u64 v[34:35], s[2:3], 0, v[32:33]
	v_lshlrev_b32_e32 v162, 1, v106
	v_lshl_add_u64 v[36:37], s[6:7], 0, v[32:33]
	v_lshl_add_u64 v[32:33], v[34:35], 0, v[162:163]
	global_load_dwordx2 v[40:41], v[32:33], off
	global_load_dwordx2 v[44:45], v[32:33], off offset:16
	global_load_dwordx2 v[50:51], v[32:33], off offset:32
	global_load_dwordx2 v[58:59], v[32:33], off offset:48
	global_load_dwordx2 v[62:63], v[32:33], off offset:64
	global_load_dwordx2 v[66:67], v[32:33], off offset:80
	global_load_dwordx2 v[70:71], v[32:33], off offset:96
	global_load_dwordx2 v[74:75], v[32:33], off offset:112
	s_waitcnt vmcnt(7)
	v_lshlrev_b32_e32 v38, 16, v40
	v_and_b32_e32 v39, 0xffff0000, v40
	v_pk_mul_f32 v[16:17], v[16:17], v[38:39]
	s_nop 0
	v_cvt_pk_bf16_f32 v34, v16, v17
	v_lshlrev_b32_e32 v16, 16, v41
	v_and_b32_e32 v17, 0xffff0000, v41
	v_pk_mul_f32 v[16:17], v[18:19], v[16:17]
	s_nop 0
	v_cvt_pk_bf16_f32 v35, v16, v17
	v_lshl_add_u64 v[16:17], v[36:37], 0, v[162:163]
	global_store_dwordx2 v[16:17], v[34:35], off
	s_waitcnt vmcnt(7)
	v_lshlrev_b32_e32 v34, 16, v44
	v_and_b32_e32 v35, 0xffff0000, v44
	v_pk_mul_f32 v[20:21], v[20:21], v[34:35]
	s_nop 0
	v_cvt_pk_bf16_f32 v18, v20, v21
	v_lshlrev_b32_e32 v20, 16, v45
	v_and_b32_e32 v21, 0xffff0000, v45
	v_pk_mul_f32 v[20:21], v[22:23], v[20:21]
	s_nop 0
	v_cvt_pk_bf16_f32 v19, v20, v21
	global_store_dwordx2 v[16:17], v[18:19], off offset:16
	s_nop 0
	s_waitcnt vmcnt(5)
	v_lshlrev_b32_e32 v20, 16, v50
	v_and_b32_e32 v21, 0xffff0000, v50
	v_pk_mul_f32 v[20:21], v[24:25], v[20:21]
	s_nop 0
	v_cvt_pk_bf16_f32 v18, v20, v21
	v_lshlrev_b32_e32 v20, 16, v51
	v_and_b32_e32 v21, 0xffff0000, v51
	v_pk_mul_f32 v[20:21], v[26:27], v[20:21]
	s_nop 0
	v_cvt_pk_bf16_f32 v19, v20, v21
	global_store_dwordx2 v[16:17], v[18:19], off offset:32
	s_nop 0
	s_waitcnt vmcnt(4)
	v_lshlrev_b32_e32 v20, 16, v58
	v_and_b32_e32 v21, 0xffff0000, v58
	v_pk_mul_f32 v[20:21], v[28:29], v[20:21]
	s_nop 0
	v_cvt_pk_bf16_f32 v18, v20, v21
	v_lshlrev_b32_e32 v20, 16, v59
	v_and_b32_e32 v21, 0xffff0000, v59
	v_pk_mul_f32 v[20:21], v[30:31], v[20:21]
	s_nop 0
	v_cvt_pk_bf16_f32 v19, v20, v21
	global_store_dwordx2 v[16:17], v[18:19], off offset:48
	s_nop 0
	s_waitcnt vmcnt(3)
	v_lshlrev_b32_e32 v20, 16, v62
	v_and_b32_e32 v21, 0xffff0000, v62
	v_lshlrev_b32_e32 v18, 16, v63
	v_and_b32_e32 v19, 0xffff0000, v63
	v_pk_mul_f32 v[0:1], v[0:1], v[20:21]
	v_pk_mul_f32 v[2:3], v[2:3], v[18:19]
	v_cvt_pk_bf16_f32 v0, v0, v1
	v_cvt_pk_bf16_f32 v1, v2, v3
	global_store_dwordx2 v[16:17], v[0:1], off offset:64
	s_nop 0
	s_waitcnt vmcnt(2)
	v_lshlrev_b32_e32 v2, 16, v66
	v_and_b32_e32 v3, 0xffff0000, v66
	v_pk_mul_f32 v[2:3], v[4:5], v[2:3]
	s_nop 0
	v_cvt_pk_bf16_f32 v0, v2, v3
	v_lshlrev_b32_e32 v2, 16, v67
	v_and_b32_e32 v3, 0xffff0000, v67
	v_pk_mul_f32 v[2:3], v[6:7], v[2:3]
	s_nop 0
	v_cvt_pk_bf16_f32 v1, v2, v3
	global_store_dwordx2 v[16:17], v[0:1], off offset:80
	s_nop 0
	s_waitcnt vmcnt(1)
	v_lshlrev_b32_e32 v2, 16, v70
	v_and_b32_e32 v3, 0xffff0000, v70
	v_pk_mul_f32 v[2:3], v[8:9], v[2:3]
	s_nop 0
	v_cvt_pk_bf16_f32 v0, v2, v3
	v_lshlrev_b32_e32 v2, 16, v71
	v_and_b32_e32 v3, 0xffff0000, v71
	v_pk_mul_f32 v[2:3], v[10:11], v[2:3]
	s_nop 0
	v_cvt_pk_bf16_f32 v1, v2, v3
	global_store_dwordx2 v[16:17], v[0:1], off offset:96
	s_nop 0
	s_waitcnt vmcnt(0)
	v_lshlrev_b32_e32 v2, 16, v74
	v_and_b32_e32 v3, 0xffff0000, v74
	v_pk_mul_f32 v[2:3], v[12:13], v[2:3]
	s_nop 0
	v_cvt_pk_bf16_f32 v0, v2, v3
	v_lshlrev_b32_e32 v2, 16, v75
	v_and_b32_e32 v3, 0xffff0000, v75
	v_pk_mul_f32 v[2:3], v[14:15], v[2:3]
	s_nop 0
	v_cvt_pk_bf16_f32 v1, v2, v3
	global_store_dwordx2 v[16:17], v[0:1], off offset:112
